# MLA S1: K fragments requested in consumption order (pairs every 2 MFMAs, lookahead 2-3 instead of 1-4); rendezvous after 16th MFMA
# speedup vs baseline: 1.1025x; 1.0192x over previous
; __device__ __forceinline__ unsigned cvt_pk_bf16(float lo, float hi) { unsigned r; asm volatile("v_cvt_pk_bf16_f32 %0, %1, %2" : "=v"(r) : "v"(lo), "v"(hi)); return r; }
; __device__ __forceinline__ bf16x8 pack8(const f32x16& p, int base) {
;     u32x4 w = {cvt_pk_bf16(p[base + 0], p[base + 1]), cvt_pk_bf16(p[base + 2], p[base + 3]), cvt_pk_bf16(p[base + 4], p[base + 5]), cvt_pk_bf16(p[base + 6], p[base + 7])};
;     return *reinterpret_cast<bf16x8*>(&w);
; }
; __device__ __forceinline__ void mla_qkt_neg(f32x16& p0, f32x16& p1, const f32x16& negm, const unsigned char* Kb, const bf16x8* qr, int r32, int hi) {
; #pragma unroll
;     for (int d0 = 0; d0 < 6; ++d0) { const int cb = (d0 * 16 + hi * 8) * 2;
;         const bf16x8 b0 = *(const bf16x8*)(Kb + r32 * KSTR + cb), b1 = *(const bf16x8*)(Kb + (32 + r32) * KSTR + cb);
;         if (d0 == 0) { p0 = __builtin_amdgcn_mfma_f32_32x32x16_bf16(b0, qr[0], negm, 0, 0, 0); p1 = __builtin_amdgcn_mfma_f32_32x32x16_bf16(b1, qr[0], negm, 0, 0, 0); }
.Lmla_nobar7:
	s_add_u32 s60, s60, 0x20000
	s_addc_u32 s61, s61, 0
	s_add_u32 s62, s62, 0x20000
	s_addc_u32 s63, s63, 0
	s_add_u32 s64, s64, 0x1000
	s_addc_u32 s65, s65, 0
	s_cmp_lt_u32 s41, s54
	s_cbranch_scc0 .Lmla_exit_pack
	ds_read_b128 v[80:83], v157
	ds_read_b128 v[150:153], v157 offset:6656
	ds_read_b128 v[146:149], v157 offset:32
	ds_read_b128 v[168:171], v157 offset:6688
	v_cvt_pk_bf16_f32 v55, v245, v246
	v_cvt_pk_bf16_f32 v54, v243, v244
	v_cvt_pk_bf16_f32 v52, v234, v240
	v_cvt_pk_bf16_f32 v53, v241, v242
	v_cvt_pk_bf16_f32 v48, v247, v248
	v_cvt_pk_bf16_f32 v49, v249, v250
	v_cvt_pk_bf16_f32 v50, v251, v252
	v_cvt_pk_bf16_f32 v51, v253, v172
	v_cvt_pk_bf16_f32 v60, v218, v219
	v_cvt_pk_bf16_f32 v61, v220, v221
	v_cvt_pk_bf16_f32 v62, v222, v223
	v_cvt_pk_bf16_f32 v63, v224, v225
	v_cvt_pk_bf16_f32 v56, v226, v227
	v_cvt_pk_bf16_f32 v57, v228, v229
	v_cvt_pk_bf16_f32 v58, v230, v231
	v_cvt_pk_bf16_f32 v59, v232, v233
	s_branch .Lmla_s1e_body
.LBB0_965:
	ds_read_b128 v[80:83], v157
	ds_read_b128 v[150:153], v157 offset:6656
	ds_read_b128 v[146:149], v157 offset:32
	ds_read_b128 v[168:171], v157 offset:6688

; __device__ __forceinline__ void mla_qkt_neg(f32x16& p0, f32x16& p1, const f32x16& negm, const unsigned char* Kb, const bf16x8* qr, int r32, int hi) {
; #pragma unroll
;     for (int d0 = 0; d0 < 6; ++d0) { const int cb = (d0 * 16 + hi * 8) * 2;
;         const bf16x8 b0 = *(const bf16x8*)(Kb + r32 * KSTR + cb), b1 = *(const bf16x8*)(Kb + (32 + r32) * KSTR + cb);
;         if (d0 == 0) { p0 = __builtin_amdgcn_mfma_f32_32x32x16_bf16(b0, qr[0], negm, 0, 0, 0); p1 = __builtin_amdgcn_mfma_f32_32x32x16_bf16(b1, qr[0], negm, 0, 0, 0); }
;         else { p0 = __builtin_amdgcn_mfma_f32_32x32x16_bf16(b0, qr[d0], p0, 0, 0, 0); p1 = __builtin_amdgcn_mfma_f32_32x32x16_bf16(b1, qr[d0], p1, 0, 0, 0); } }
; }
; __device__ __forceinline__ void pv_both_kp(f32x16& o0, f32x16& o1, int vb, bf16x8 pa0, bf16x8 pa1, bf16x8 pa2, bf16x8 pa3) {
;     const s16x4 l0 = tr_read<v_rd_off_kp(0, 0, 0)>(vb), h0 = tr_read<v_rd_off_kp(0, 0, 1)>(vb), l1 = tr_read<v_rd_off_kp(0, 1, 0)>(vb), h1 = tr_read<v_rd_off_kp(0, 1, 1)>(vb);
;     const s16x4 l2 = tr_read<v_rd_off_kp(0, 2, 0)>(vb), h2 = tr_read<v_rd_off_kp(0, 2, 1)>(vb), l3 = tr_read<v_rd_off_kp(0, 3, 0)>(vb), h3 = tr_read<v_rd_off_kp(0, 3, 1)>(vb);
;     const s16x4 m0 = tr_read<v_rd_off_kp(1, 0, 0)>(vb), n0 = tr_read<v_rd_off_kp(1, 0, 1)>(vb), m1 = tr_read<v_rd_off_kp(1, 1, 0)>(vb), n1 = tr_read<v_rd_off_kp(1, 1, 1)>(vb);
;     const s16x4 m2 = tr_read<v_rd_off_kp(1, 2, 0)>(vb), n2 = tr_read<v_rd_off_kp(1, 2, 1)>(vb), m3 = tr_read<v_rd_off_kp(1, 3, 0)>(vb), n3 = tr_read<v_rd_off_kp(1, 3, 1)>(vb);
;     asm volatile("s_waitcnt lgkmcnt(8)" ::: "memory"); __builtin_amdgcn_sched_barrier(0);
;     ...
;     o0 = __builtin_amdgcn_mfma_f32_32x32x16_bf16(pa0, PK(l0, h0), o0, 0, 0, 0);
;     o0 = __builtin_amdgcn_mfma_f32_32x32x16_bf16(pa1, PK(l1, h1), o0, 0, 0, 0);
;     o0 = __builtin_amdgcn_mfma_f32_32x32x16_bf16(pa2, PK(l2, h2), o0, 0, 0, 0);
;     o0 = __builtin_amdgcn_mfma_f32_32x32x16_bf16(pa3, PK(l3, h3), o0, 0, 0, 0);
;     asm volatile("s_waitcnt lgkmcnt(0)" ::: "memory"); __builtin_amdgcn_sched_barrier(0);
;     o1 = __builtin_amdgcn_mfma_f32_32x32x16_bf16(pa0, PK(m0, n0), o1, 0, 0, 0);
;     o1 = __builtin_amdgcn_mfma_f32_32x32x16_bf16(pa1, PK(m1, n1), o1, 0, 0, 0);
;     o1 = __builtin_amdgcn_mfma_f32_32x32x16_bf16(pa2, PK(m2, n2), o1, 0, 0, 0);
;     o1 = __builtin_amdgcn_mfma_f32_32x32x16_bf16(pa3, PK(m3, n3), o1, 0, 0, 0);
;     ...
; }
.LBB0_969:
	s_waitcnt lgkmcnt(3)
	v_mfma_f32_32x32x16_bf16 v[64:79], v[80:83], v[96:99], v[32:47]
	s_waitcnt lgkmcnt(2)
	v_mfma_f32_32x32x16_bf16 v[80:95], v[150:153], v[96:99], v[32:47]
	s_waitcnt lgkmcnt(1)
	v_mfma_f32_32x32x16_bf16 v[64:79], v[146:149], v[100:103], v[64:79]
	ds_read_b128 v[162:165], v157 offset:64
	ds_read_b128 v[150:153], v157 offset:6720
	s_waitcnt lgkmcnt(2)
	v_mfma_f32_32x32x16_bf16 v[80:95], v[168:171], v[100:103], v[80:95]
	s_waitcnt lgkmcnt(1)
	v_mfma_f32_32x32x16_bf16 v[64:79], v[162:165], v[104:107], v[64:79]
	ds_read_b128 v[146:149], v157 offset:96
	ds_read_b128 v[168:171], v157 offset:6752
	s_waitcnt lgkmcnt(2)
	v_mfma_f32_32x32x16_bf16 v[80:95], v[150:153], v[104:107], v[80:95]
	s_waitcnt lgkmcnt(1)
	v_mfma_f32_32x32x16_bf16 v[64:79], v[146:149], v[108:111], v[64:79]
	ds_read_b128 v[162:165], v157 offset:128
	ds_read_b128 v[150:153], v157 offset:6784
	s_waitcnt lgkmcnt(2)
	v_mfma_f32_32x32x16_bf16 v[80:95], v[168:171], v[108:111], v[80:95]
	s_waitcnt lgkmcnt(1)
	v_mfma_f32_32x32x16_bf16 v[64:79], v[162:165], v[112:115], v[64:79]
	ds_read_b128 v[168:171], v157 offset:160
	ds_read_b128 v[162:165], v157 offset:6816
	ds_read_b64_tr_b16 v[182:183], v204 offset:0
	ds_read_b64_tr_b16 v[184:185], v204 offset:0x100
	s_waitcnt lgkmcnt(4)
	v_mfma_f32_32x32x16_bf16 v[80:95], v[150:153], v[112:115], v[80:95]
	ds_read_b64_tr_b16 v[146:147], v204 offset:0x800
	ds_read_b64_tr_b16 v[148:149], v204 offset:0x900
	ds_read_b64_tr_b16 v[186:187], v204 offset:0x1000
	ds_read_b64_tr_b16 v[188:189], v204 offset:0x1100
	ds_read_b64_tr_b16 v[190:191], v204 offset:0x1800
	ds_read_b64_tr_b16 v[192:193], v204 offset:0x1900
	ds_read_b64_tr_b16 v[206:207], v204 offset:0x200
	ds_read_b64_tr_b16 v[208:209], v204 offset:0x300
	s_waitcnt lgkmcnt(11)
	v_mfma_f32_32x32x16_bf16 v[64:79], v[168:171], v[116:119], v[64:79]
	ds_read_b64_tr_b16 v[150:151], v204 offset:0xa00
	ds_read_b64_tr_b16 v[152:153], v204 offset:0xb00
	ds_read_b64_tr_b16 v[210:211], v204 offset:0x1200
	ds_read_b64_tr_b16 v[212:213], v204 offset:0x1300
	ds_read_b64_tr_b16 v[214:215], v204 offset:0x1a00
	ds_read_b64_tr_b16 v[216:217], v204 offset:0x1b00
	s_waitcnt lgkmcnt(0)
	v_mfma_f32_32x32x16_bf16 v[80:95], v[162:165], v[116:119], v[80:95]
	v_mfma_f32_32x32x16_bf16 v[0:15], v[60:63], v[182:185], v[0:15]
	v_mfma_f32_32x32x16_bf16 v[0:15], v[56:59], v[146:149], v[0:15]
	v_mfma_f32_32x32x16_bf16 v[0:15], v[52:55], v[186:189], v[0:15]
	v_mfma_f32_32x32x16_bf16 v[0:15], v[48:51], v[190:193], v[0:15]
	s_waitcnt lgkmcnt(0)
	s_cmp_lg_u32 s40, 0
	s_cbranch_scc0 .Lmla_nobar4
	s_barrier
.Lmla_nobar4:
	v_mfma_f32_32x32x16_bf16 v[16:31], v[60:63], v[206:209], v[16:31]
	v_mfma_f32_32x32x16_bf16 v[16:31], v[56:59], v[150:153], v[16:31]
	v_mfma_f32_32x32x16_bf16 v[16:31], v[52:55], v[210:213], v[16:31]
	v_mfma_f32_32x32x16_bf16 v[16:31], v[48:51], v[214:217], v[16:31]
	s_cmp_lg_u64 s[44:45], 0
	s_cbranch_scc0 .Lmla_w1_tail
	s_waitcnt vmcnt(3)
	ds_write_b128 v196, v[120:123]
	ds_write_b128 v197, v[128:131] offset:26624
	s_cmp_lg_u32 s8, 0
	s_cbranch_scc0 .LBB0_975
	ds_write_b128 v238, v[124:127] offset:128

; __device__ __forceinline__ unsigned cvt_pk_bf16(float lo, float hi) { unsigned r; asm volatile("v_cvt_pk_bf16_f32 %0, %1, %2" : "=v"(r) : "v"(lo), "v"(hi)); return r; }
; __device__ __forceinline__ bf16x8 pack8(const f32x16& p, int base) {
;     u32x4 w = {cvt_pk_bf16(p[base + 0], p[base + 1]), cvt_pk_bf16(p[base + 2], p[base + 3]), cvt_pk_bf16(p[base + 4], p[base + 5]), cvt_pk_bf16(p[base + 6], p[base + 7])};
;     return *reinterpret_cast<bf16x8*>(&w);
; }
.Lmla_nobar5:
	ds_read_b128 v[168:171], v157 offset:13312
	ds_read_b128 v[162:165], v157 offset:19968
	v_cvt_pk_bf16_f32 v87, v245, v246
	v_cvt_pk_bf16_f32 v86, v243, v244
	v_cvt_pk_bf16_f32 v85, v241, v242
	v_cvt_pk_bf16_f32 v84, v234, v240
	v_cvt_pk_bf16_f32 v82, v251, v252
	v_cvt_pk_bf16_f32 v83, v253, v172
	v_cvt_pk_bf16_f32 v80, v247, v248
	v_cvt_pk_bf16_f32 v81, v249, v250
	v_cvt_pk_bf16_f32 v92, v218, v219
	v_cvt_pk_bf16_f32 v93, v220, v221
	v_cvt_pk_bf16_f32 v94, v222, v223
	v_cvt_pk_bf16_f32 v95, v224, v225
	v_cvt_pk_bf16_f32 v88, v226, v227
	v_cvt_pk_bf16_f32 v89, v228, v229
	v_cvt_pk_bf16_f32 v90, v230, v231
	v_cvt_pk_bf16_f32 v91, v232, v233
	s_add_u32 s60, s60, 0x20000
	s_addc_u32 s61, s61, 0
	s_add_u32 s62, s62, 0x20000
	s_addc_u32 s63, s63, 0
	s_add_u32 s64, s64, 0x1000
	s_addc_u32 s65, s65, 0
	s_add_i32 s47, s47, 3
	s_cmp_ge_i32 s47, s54
	s_cbranch_scc1 .LBB0_983
	global_load_dwordx4 v[120:123], v166, s[60:61]
	global_load_dwordx4 v[124:127], v167, s[64:65]

; __device__ __forceinline__ void mla_qkt_neg(f32x16& p0, f32x16& p1, const f32x16& negm, const unsigned char* Kb, const bf16x8* qr, int r32, int hi) {
; #pragma unroll
;     for (int d0 = 0; d0 < 6; ++d0) { const int cb = (d0 * 16 + hi * 8) * 2;
;         const bf16x8 b0 = *(const bf16x8*)(Kb + r32 * KSTR + cb), b1 = *(const bf16x8*)(Kb + (32 + r32) * KSTR + cb);
;         if (d0 == 0) { p0 = __builtin_amdgcn_mfma_f32_32x32x16_bf16(b0, qr[0], negm, 0, 0, 0); p1 = __builtin_amdgcn_mfma_f32_32x32x16_bf16(b1, qr[0], negm, 0, 0, 0); }
;         else { p0 = __builtin_amdgcn_mfma_f32_32x32x16_bf16(b0, qr[d0], p0, 0, 0, 0); p1 = __builtin_amdgcn_mfma_f32_32x32x16_bf16(b1, qr[d0], p1, 0, 0, 0); } }
; }
; __device__ __forceinline__ void pv_both_kp(f32x16& o0, f32x16& o1, int vb, bf16x8 pa0, bf16x8 pa1, bf16x8 pa2, bf16x8 pa3) {
;     const s16x4 l0 = tr_read<v_rd_off_kp(0, 0, 0)>(vb), h0 = tr_read<v_rd_off_kp(0, 0, 1)>(vb), l1 = tr_read<v_rd_off_kp(0, 1, 0)>(vb), h1 = tr_read<v_rd_off_kp(0, 1, 1)>(vb);
;     const s16x4 l2 = tr_read<v_rd_off_kp(0, 2, 0)>(vb), h2 = tr_read<v_rd_off_kp(0, 2, 1)>(vb), l3 = tr_read<v_rd_off_kp(0, 3, 0)>(vb), h3 = tr_read<v_rd_off_kp(0, 3, 1)>(vb);
;     const s16x4 m0 = tr_read<v_rd_off_kp(1, 0, 0)>(vb), n0 = tr_read<v_rd_off_kp(1, 0, 1)>(vb), m1 = tr_read<v_rd_off_kp(1, 1, 0)>(vb), n1 = tr_read<v_rd_off_kp(1, 1, 1)>(vb);
;     const s16x4 m2 = tr_read<v_rd_off_kp(1, 2, 0)>(vb), n2 = tr_read<v_rd_off_kp(1, 2, 1)>(vb), m3 = tr_read<v_rd_off_kp(1, 3, 0)>(vb), n3 = tr_read<v_rd_off_kp(1, 3, 1)>(vb);
;     asm volatile("s_waitcnt lgkmcnt(8)" ::: "memory"); __builtin_amdgcn_sched_barrier(0);
;     ...
;     o0 = __builtin_amdgcn_mfma_f32_32x32x16_bf16(pa0, PK(l0, h0), o0, 0, 0, 0);
;     o0 = __builtin_amdgcn_mfma_f32_32x32x16_bf16(pa1, PK(l1, h1), o0, 0, 0, 0);
;     o0 = __builtin_amdgcn_mfma_f32_32x32x16_bf16(pa2, PK(l2, h2), o0, 0, 0, 0);
;     o0 = __builtin_amdgcn_mfma_f32_32x32x16_bf16(pa3, PK(l3, h3), o0, 0, 0, 0);
;     asm volatile("s_waitcnt lgkmcnt(0)" ::: "memory"); __builtin_amdgcn_sched_barrier(0);
;     o1 = __builtin_amdgcn_mfma_f32_32x32x16_bf16(pa0, PK(m0, n0), o1, 0, 0, 0);
;     o1 = __builtin_amdgcn_mfma_f32_32x32x16_bf16(pa1, PK(m1, n1), o1, 0, 0, 0);
;     o1 = __builtin_amdgcn_mfma_f32_32x32x16_bf16(pa2, PK(m2, n2), o1, 0, 0, 0);
;     o1 = __builtin_amdgcn_mfma_f32_32x32x16_bf16(pa3, PK(m3, n3), o1, 0, 0, 0);
;     ...
; }
.LBB0_985:
	s_waitcnt lgkmcnt(1)
	v_mfma_f32_32x32x16_bf16 v[64:79], v[168:171], v[96:99], v[32:47]
	ds_read_b128 v[146:149], v157 offset:13344
	ds_read_b128 v[150:153], v157 offset:20000
	s_waitcnt lgkmcnt(2)
	v_mfma_f32_32x32x16_bf16 v[48:63], v[162:165], v[96:99], v[32:47]
	s_waitcnt lgkmcnt(1)
	v_mfma_f32_32x32x16_bf16 v[64:79], v[146:149], v[100:103], v[64:79]
	ds_read_b128 v[168:171], v157 offset:13376
	ds_read_b128 v[162:165], v157 offset:20032
	s_waitcnt lgkmcnt(2)
	v_mfma_f32_32x32x16_bf16 v[48:63], v[150:153], v[100:103], v[48:63]
	s_waitcnt lgkmcnt(1)
	v_mfma_f32_32x32x16_bf16 v[64:79], v[168:171], v[104:107], v[64:79]
	ds_read_b128 v[146:149], v157 offset:13408
	ds_read_b128 v[150:153], v157 offset:20064
	s_waitcnt lgkmcnt(2)
	v_mfma_f32_32x32x16_bf16 v[48:63], v[162:165], v[104:107], v[48:63]
	s_waitcnt lgkmcnt(1)
	v_mfma_f32_32x32x16_bf16 v[64:79], v[146:149], v[108:111], v[64:79]
	ds_read_b128 v[168:171], v157 offset:13440
	ds_read_b128 v[162:165], v157 offset:20096
	s_waitcnt lgkmcnt(2)
	v_mfma_f32_32x32x16_bf16 v[48:63], v[150:153], v[108:111], v[48:63]
	s_waitcnt lgkmcnt(1)
	v_mfma_f32_32x32x16_bf16 v[64:79], v[168:171], v[112:115], v[64:79]
	ds_read_b128 v[150:153], v157 offset:13472
	ds_read_b128 v[172:175], v157 offset:20128
	ds_read_b64_tr_b16 v[168:169], v199 offset:0
	ds_read_b64_tr_b16 v[170:171], v199 offset:0x100
	s_waitcnt lgkmcnt(4)
	v_mfma_f32_32x32x16_bf16 v[48:63], v[162:165], v[112:115], v[48:63]
	ds_read_b64_tr_b16 v[146:147], v199 offset:0x800
	ds_read_b64_tr_b16 v[148:149], v199 offset:0x900
	ds_read_b64_tr_b16 v[182:183], v199 offset:0x1000
	ds_read_b64_tr_b16 v[184:185], v199 offset:0x1100
	ds_read_b64_tr_b16 v[186:187], v199 offset:0x1800
	ds_read_b64_tr_b16 v[188:189], v199 offset:0x1900
	ds_read_b64_tr_b16 v[190:191], v199 offset:0x200
	ds_read_b64_tr_b16 v[192:193], v199 offset:0x300
	s_waitcnt lgkmcnt(11)
	v_mfma_f32_32x32x16_bf16 v[64:79], v[150:153], v[116:119], v[64:79]
	ds_read_b64_tr_b16 v[150:151], v199 offset:0xa00
	ds_read_b64_tr_b16 v[152:153], v199 offset:0xb00
	ds_read_b64_tr_b16 v[208:209], v199 offset:0x1200
	ds_read_b64_tr_b16 v[210:211], v199 offset:0x1300
	ds_read_b64_tr_b16 v[212:213], v199 offset:0x1a00
	ds_read_b64_tr_b16 v[214:215], v199 offset:0x1b00
	s_waitcnt lgkmcnt(0)
	v_mfma_f32_32x32x16_bf16 v[48:63], v[172:175], v[116:119], v[48:63]
	v_mfma_f32_32x32x16_bf16 v[0:15], v[92:95], v[168:171], v[0:15]
	v_mfma_f32_32x32x16_bf16 v[0:15], v[88:91], v[146:149], v[0:15]
	v_mfma_f32_32x32x16_bf16 v[0:15], v[84:87], v[182:185], v[0:15]
	v_mfma_f32_32x32x16_bf16 v[0:15], v[80:83], v[186:189], v[0:15]
	s_waitcnt lgkmcnt(0)
	s_cmp_lg_u32 s40, 0
	s_cbranch_scc0 .Lmla_nobar6
	s_barrier
.Lmla_nobar6:
	v_mfma_f32_32x32x16_bf16 v[16:31], v[92:95], v[190:193], v[16:31]
	v_mfma_f32_32x32x16_bf16 v[16:31], v[88:91], v[150:153], v[16:31]
	v_mfma_f32_32x32x16_bf16 v[16:31], v[84:87], v[208:211], v[16:31]
	v_mfma_f32_32x32x16_bf16 v[16:31], v[80:83], v[212:215], v[16:31]
	s_cmp_lt_i32 s47, s54
	s_cbranch_scc0 .Lmla_w2_tail
	s_waitcnt vmcnt(3)
	ds_write_b128 v200, v[136:139]
	ds_write_b128 v201, v[132:135] offset:26624
	s_cmp_lg_u32 s8, 0
	s_cbranch_scc0 .LBB0_991
	ds_write_b128 v239, v[140:143] offset:128
